# mixer-B unit epilogue: 64 two-byte stores per lane replaced by LDS-staged tile + 8 global_store_dwordx4
# baseline (speedup 1.0000x reference)
; __device__ __forceinline__ void unit(LAS unsigned char* lds, const bf16* __restrict__ PROJ, bf16* __restrict__ MIXED, const float* __restrict__ subln_g, float lam, int R0, int seq, int h, int qb) {
;     ...
;     if (c == 0) {
;         float sq[16];
; #pragma unroll
;         for (int r = 0; r < 16; ++r) { float s = 0.f;
; #pragma unroll
;             for (int d = 0; d < 4; ++d) { const float a = o[d][r] * rli[r] - lam * xch[(d * 16 + r) * 64 + lane]; o[d][r] = a; s += a * a; }
;             sq[r] = s; }
.LBB0_294:
	s_andn2_b64 vcc, exec, s[4:5]
	s_waitcnt lgkmcnt(0)
	s_barrier
	s_cbranch_vccnz .LBB0_249
	ds_read2st64_b32 v[64:65], v98 offset1:1
	ds_read2st64_b32 v[66:67], v98 offset0:16 offset1:17
	ds_read2st64_b32 v[68:69], v98 offset0:2 offset1:3
	ds_read2st64_b32 v[76:77], v98 offset0:4 offset1:5
	ds_read2st64_b32 v[70:71], v98 offset0:6 offset1:7
	ds_read2st64_b32 v[108:109], v98 offset0:18 offset1:19
	ds_read2st64_b32 v[110:111], v98 offset0:20 offset1:21
	ds_read2st64_b32 v[72:73], v98 offset0:22 offset1:23
	ds_read2st64_b32 v[82:83], v98 offset0:32 offset1:33
	ds_read2st64_b32 v[112:113], v98 offset0:34 offset1:35
	ds_read2st64_b32 v[114:115], v98 offset0:36 offset1:37
	ds_read2st64_b32 v[74:75], v98 offset0:38 offset1:39
	ds_read2st64_b32 v[100:101], v98 offset0:48 offset1:49
	s_waitcnt lgkmcnt(12)
	v_mul_f32_e32 v64, v173, v64
	v_fma_f32 v85, v0, v80, -v64
	s_waitcnt lgkmcnt(11)
	v_mul_f32_e32 v0, v173, v66
	v_fma_f32 v87, v48, v80, -v0
	s_waitcnt lgkmcnt(4)
	v_mul_f32_e32 v0, v173, v82
	v_fma_f32 v89, v32, v80, -v0
	s_waitcnt lgkmcnt(0)
	v_mul_f32_e32 v0, v173, v100
	v_fma_f32 v88, v16, v80, -v0
	v_mul_f32_e32 v0, v173, v65
	v_fma_f32 v86, v1, v79, -v0
	v_mul_f32_e32 v0, v173, v67
	v_fma_f32 v84, v49, v79, -v0
	v_mul_f32_e32 v0, v173, v83
	v_fma_f32 v83, v33, v79, -v0
	v_mul_f32_e32 v0, v173, v101
	ds_read2st64_b32 v[116:117], v98 offset0:50 offset1:51
	ds_read2st64_b32 v[118:119], v98 offset0:52 offset1:53
	ds_read2st64_b32 v[120:121], v98 offset0:54 offset1:55
	v_fma_f32 v82, v17, v79, -v0
	v_mul_f32_e32 v0, v173, v68
	v_fma_f32 v81, v2, v78, -v0
	v_mul_f32_e32 v0, v173, v108
	v_fma_f32 v80, v50, v78, -v0
	v_mul_f32_e32 v0, v173, v112
	v_fma_f32 v79, v34, v78, -v0
	s_waitcnt lgkmcnt(2)
	v_mul_f32_e32 v0, v173, v116
	v_fma_f32 v78, v18, v78, -v0
	v_mul_f32_e32 v0, v173, v69
	v_fma_f32 v68, v3, v102, -v0
	v_mul_f32_e32 v0, v173, v109
	v_fma_f32 v67, v51, v102, -v0
	v_mul_f32_e32 v0, v173, v113
	v_fma_f32 v66, v35, v102, -v0
	v_mul_f32_e32 v0, v173, v117
	v_fma_f32 v65, v19, v102, -v0
	v_mul_f32_e32 v0, v173, v76
	v_fma_f32 v64, v4, v107, -v0
	v_mul_f32_e32 v0, v173, v110
	v_fma_f32 v52, v52, v107, -v0
	v_mul_f32_e32 v0, v173, v114
	v_fma_f32 v51, v36, v107, -v0
	s_waitcnt lgkmcnt(1)
	v_mul_f32_e32 v0, v173, v118
	v_fma_f32 v50, v20, v107, -v0
	v_mul_f32_e32 v0, v173, v77
	v_fma_f32 v49, v5, v106, -v0
	v_mul_f32_e32 v0, v173, v111
	v_fma_f32 v48, v53, v106, -v0
	v_mul_f32_e32 v0, v173, v115
	v_fma_f32 v37, v37, v106, -v0
	v_mul_f32_e32 v0, v173, v119
	v_fma_f32 v33, v21, v106, -v0
	v_mul_f32_e32 v0, v173, v70
	v_fma_f32 v32, v6, v105, -v0
	v_mul_f32_e32 v0, v173, v72
	v_fma_f32 v21, v54, v105, -v0
	v_mul_f32_e32 v0, v173, v74
	v_fma_f32 v20, v38, v105, -v0
	s_waitcnt lgkmcnt(0)
	v_mul_f32_e32 v0, v173, v120
	v_fma_f32 v38, v22, v105, -v0
	v_mul_f32_e32 v0, v173, v71
	v_fma_f32 v36, v7, v104, -v0
	v_mul_f32_e32 v0, v173, v73
	v_fma_f32 v34, v55, v104, -v0
	v_mul_f32_e32 v0, v173, v75
	v_fma_f32 v35, v39, v104, -v0
	v_mul_f32_e32 v0, v173, v121
	v_fma_f32 v22, v23, v104, -v0
	ds_read2st64_b32 v[0:1], v98 offset0:8 offset1:9
	ds_read2st64_b32 v[2:3], v98 offset0:10 offset1:11
	ds_read2st64_b32 v[18:19], v98 offset0:12 offset1:13
	ds_read2st64_b32 v[4:5], v98 offset0:14 offset1:15
	ds_read2st64_b32 v[54:55], v98 offset0:24 offset1:25
	ds_read2st64_b32 v[106:107], v98 offset0:26 offset1:27
	ds_read2st64_b32 v[108:109], v98 offset0:28 offset1:29
	ds_read2st64_b32 v[6:7], v98 offset0:30 offset1:31
	ds_read2st64_b32 v[74:75], v98 offset0:40 offset1:41
	ds_read2st64_b32 v[110:111], v98 offset0:42 offset1:43
	ds_read2st64_b32 v[112:113], v98 offset0:44 offset1:45
	ds_read2st64_b32 v[16:17], v98 offset0:46 offset1:47
	ds_read2st64_b32 v[114:115], v98 offset0:56 offset1:57
	ds_read2st64_b32 v[116:117], v98 offset0:58 offset1:59
	ds_read2st64_b32 v[118:119], v98 offset0:60 offset1:61
	ds_read2st64_b32 v[120:121], v98 offset0:62 offset1:63
	s_waitcnt lgkmcnt(14)
	v_mul_f32_e32 v1, v173, v1
	v_mul_f32_e32 v2, v173, v2
	v_mul_f32_e32 v0, v173, v0
	v_fma_f32 v71, v9, v96, -v1
	s_waitcnt lgkmcnt(11)
	v_mul_f32_e32 v1, v173, v55
	v_fma_f32 v55, v10, v95, -v2
	s_waitcnt lgkmcnt(10)
	v_mul_f32_e32 v2, v173, v106
	v_fma_f32 v69, v8, v97, -v0
	v_mul_f32_e32 v0, v173, v54
	s_waitcnt lgkmcnt(7)
	v_mul_f32_e32 v8, v173, v74
	v_fma_f32 v54, v58, v95, -v2
	s_waitcnt lgkmcnt(6)
	v_mul_f32_e32 v2, v173, v110
	v_fma_f32 v74, v40, v97, -v8
	s_waitcnt lgkmcnt(3)
	v_mul_f32_e32 v8, v173, v114
	v_fma_f32 v53, v42, v95, -v2
	s_waitcnt lgkmcnt(2)
	v_mul_f32_e32 v2, v173, v116
	v_fma_f32 v73, v24, v97, -v8
	v_mul_f32_e32 v8, v173, v75
	v_fma_f32 v42, v26, v95, -v2
	v_mul_f32_e32 v2, v173, v3
	v_fma_f32 v70, v57, v96, -v1
	v_fma_f32 v57, v41, v96, -v8
	v_fma_f32 v41, v11, v94, -v2
	v_mul_f32_e32 v2, v173, v107
	v_fma_f32 v40, v59, v94, -v2
	v_mul_f32_e32 v2, v173, v111
	v_fma_f32 v39, v43, v94, -v2
	v_mul_f32_e32 v2, v173, v117
	v_mul_f32_e32 v8, v173, v115
	v_fma_f32 v26, v27, v94, -v2
	v_mul_f32_e32 v2, v173, v18
	v_fma_f32 v72, v56, v97, -v0
	v_fma_f32 v56, v25, v96, -v8
	v_fma_f32 v25, v12, v93, -v2
	v_mul_f32_e32 v2, v173, v108
	v_fma_f32 v24, v60, v93, -v2
	v_mul_f32_e32 v2, v173, v112
	v_fma_f32 v23, v44, v93, -v2
	s_waitcnt lgkmcnt(1)
; __device__ __forceinline__ void unit(LAS unsigned char* lds, const bf16* __restrict__ PROJ, bf16* __restrict__ MIXED, const float* __restrict__ subln_g, float lam, int R0, int seq, int h, int qb) {
;     ...
;         for (int r = 0; r < 16; ++r) { float s = 0.f;
; #pragma unroll
;             for (int d = 0; d < 4; ++d) { const float a = o[d][r] * rli[r] - lam * xch[(d * 16 + r) * 64 + lane]; o[d][r] = a; s += a * a; }
;             sq[r] = s; }
; #pragma unroll
;         for (int off = 1; off < 32; off <<= 1)
; #pragma unroll
;             for (int r = 0; r < 16; ++r) sq[r] += __shfl_xor(sq[r], off);
;         float gv[4];
; #pragma unroll
;         for (int d = 0; d < 4; ++d) gv[d] = subln_g[32 * d + r32] * 0.8f;
	v_mul_f32_e32 v2, v173, v118
	v_fma_f32 v18, v28, v93, -v2
	v_mul_f32_e32 v2, v173, v19
	v_fma_f32 v12, v13, v92, -v2
	v_mul_f32_e32 v2, v173, v109
	v_mul_f32_e32 v101, v80, v80
	v_fma_f32 v11, v61, v92, -v2
	v_mul_f32_e32 v2, v173, v113
	v_fmac_f32_e32 v101, v81, v81
	v_mul_f32_e32 v19, v11, v11
	v_fma_f32 v10, v45, v92, -v2
	v_mul_f32_e32 v2, v173, v119
	v_fmac_f32_e32 v101, v79, v79
	v_fmac_f32_e32 v19, v12, v12
	v_fma_f32 v8, v29, v92, -v2
	v_mul_f32_e32 v2, v173, v4
	v_fmac_f32_e32 v101, v78, v78
	v_fmac_f32_e32 v19, v10, v10
	v_fma_f32 v4, v14, v91, -v2
	v_mul_f32_e32 v2, v173, v6
	v_mul_f32_e32 v103, v67, v67
	v_fmac_f32_e32 v19, v8, v8
	v_fma_f32 v3, v62, v91, -v2
	ds_bpermute_b32 v28, v192, v101
	v_fmac_f32_e32 v103, v68, v68
	v_mul_f32_e32 v105, v34, v34
	v_mul_f32_e32 v1, v70, v70
	v_mul_f32_e32 v14, v3, v3
	v_mul_f32_e32 v2, v173, v16
	ds_bpermute_b32 v60, v192, v19
	v_fmac_f32_e32 v103, v66, v66
	v_fmac_f32_e32 v105, v36, v36
	v_fmac_f32_e32 v1, v71, v71
	v_fmac_f32_e32 v14, v4, v4
	v_fma_f32 v2, v46, v91, -v2
	s_waitcnt lgkmcnt(2)
	v_mul_f32_e32 v6, v173, v120
	v_fmac_f32_e32 v103, v65, v65
	v_fmac_f32_e32 v105, v35, v35
	v_fmac_f32_e32 v1, v57, v57
	v_fmac_f32_e32 v14, v2, v2
	v_fma_f32 v13, v30, v91, -v6
	v_fmac_f32_e32 v105, v22, v22
	v_fmac_f32_e32 v1, v56, v56
	v_fmac_f32_e32 v14, v13, v13
	ds_bpermute_b32 v29, v192, v103
	v_mul_f32_e32 v100, v84, v84
	v_mul_f32_e32 v0, v72, v72
	s_waitcnt lgkmcnt(2)
	v_add_f32_e32 v28, v101, v28
	ds_bpermute_b32 v44, v192, v105
	ds_bpermute_b32 v46, v192, v1
	ds_bpermute_b32 v61, v192, v14
	v_fmac_f32_e32 v100, v86, v86
	v_fmac_f32_e32 v0, v69, v69
	v_mul_f32_e32 v59, v40, v40
	v_mul_f32_e32 v27, v24, v24
	s_waitcnt lgkmcnt(4)
	v_add_f32_e32 v19, v19, v60
	ds_bpermute_b32 v60, v193, v28
	v_fmac_f32_e32 v100, v83, v83
	v_fmac_f32_e32 v0, v74, v74
	v_fmac_f32_e32 v59, v41, v41
	v_fmac_f32_e32 v27, v25, v25
	v_mul_f32_e32 v5, v173, v5
	v_fmac_f32_e32 v100, v82, v82
	v_fmac_f32_e32 v0, v73, v73
	v_fmac_f32_e32 v59, v39, v39
	v_fmac_f32_e32 v27, v23, v23
	v_fma_f32 v9, v15, v90, -v5
	v_mul_f32_e32 v5, v173, v7
	v_fmac_f32_e32 v59, v26, v26
	v_fmac_f32_e32 v27, v18, v18
	v_fma_f32 v6, v63, v90, -v5
	v_mul_f32_e32 v5, v173, v17
	ds_bpermute_b32 v17, v192, v100
	s_waitcnt lgkmcnt(5)
	v_add_f32_e32 v29, v103, v29
	ds_bpermute_b32 v45, v192, v0
	v_mul_f32_e32 v77, v21, v21
	v_fma_f32 v7, v47, v90, -v5
	s_waitcnt lgkmcnt(5)
	v_add_f32_e32 v44, v105, v44
	s_waitcnt lgkmcnt(4)
	v_add_f32_e32 v1, v1, v46
	ds_bpermute_b32 v46, v192, v59
	ds_bpermute_b32 v47, v192, v27
	s_waitcnt lgkmcnt(5)
	v_add_f32_e32 v14, v14, v61
	ds_bpermute_b32 v61, v193, v29
	v_fmac_f32_e32 v77, v32, v32
	s_waitcnt lgkmcnt(5)
	v_add_f32_e32 v28, v28, v60
	ds_bpermute_b32 v60, v193, v44
	v_fmac_f32_e32 v77, v20, v20
	v_fmac_f32_e32 v77, v38, v38
	s_waitcnt lgkmcnt(5)
	v_add_f32_e32 v17, v100, v17
	ds_bpermute_b32 v43, v192, v77
	s_waitcnt lgkmcnt(5)
	v_add_f32_e32 v0, v0, v45
	s_waitcnt lgkmcnt(4)
	v_add_f32_e32 v46, v59, v46
	s_waitcnt lgkmcnt(3)
	v_add_f32_e32 v27, v27, v47
	ds_bpermute_b32 v59, v193, v17
	s_waitcnt lgkmcnt(3)
	v_add_f32_e32 v29, v29, v61
	ds_bpermute_b32 v61, v193, v0
	s_waitcnt lgkmcnt(3)
	v_add_f32_e32 v44, v44, v60
	ds_bpermute_b32 v60, v193, v27
	s_waitcnt lgkmcnt(3)
	v_add_f32_e32 v43, v77, v43
	s_waitcnt lgkmcnt(2)
	v_add_f32_e32 v17, v17, v59
	ds_bpermute_b32 v59, v193, v43
	s_waitcnt lgkmcnt(2)
	v_add_f32_e32 v0, v0, v61
	ds_bpermute_b32 v61, v193, v19
	s_waitcnt lgkmcnt(2)
	v_add_f32_e32 v27, v27, v60
	ds_bpermute_b32 v60, v194, v17
	s_waitcnt lgkmcnt(2)
	v_add_f32_e32 v43, v43, v59
	ds_bpermute_b32 v59, v193, v46
	s_waitcnt lgkmcnt(2)
	v_add_f32_e32 v19, v19, v61
	ds_bpermute_b32 v61, v194, v28
	s_waitcnt lgkmcnt(2)
	v_add_f32_e32 v17, v17, v60
	ds_bpermute_b32 v60, v194, v43
	s_waitcnt lgkmcnt(2)
	v_add_f32_e32 v46, v46, v59
	v_mul_f32_e32 v102, v52, v52
	s_waitcnt lgkmcnt(1)
	v_add_f32_e32 v28, v28, v61
	ds_bpermute_b32 v61, v194, v44
	s_waitcnt lgkmcnt(1)
	v_add_f32_e32 v43, v43, v60
	ds_bpermute_b32 v60, v194, v46
	v_fmac_f32_e32 v102, v64, v64
	v_mul_f32_e32 v15, v6, v6
	s_waitcnt lgkmcnt(1)
	v_add_f32_e32 v44, v44, v61
	global_load_dword v61, v[162:163], off
	s_waitcnt lgkmcnt(0)
	v_add_f32_e32 v46, v46, v60
	global_load_dword v60, v[162:163], off offset:128
	global_load_dword v62, v[162:163], off offset:256
	global_load_dword v63, v[162:163], off offset:384
	v_fmac_f32_e32 v102, v51, v51
	v_fmac_f32_e32 v15, v9, v9
	v_mul_f32_e32 v5, v173, v121
	v_fmac_f32_e32 v102, v50, v50
	v_fmac_f32_e32 v15, v7, v7
	v_fma_f32 v5, v31, v90, -v5
	v_mul_f32_e32 v99, v87, v87
	v_fmac_f32_e32 v15, v5, v5
	ds_bpermute_b32 v30, v192, v102
	v_fmac_f32_e32 v99, v85, v85
	v_mul_f32_e32 v58, v54, v54
	ds_bpermute_b32 v47, v192, v15
	v_fmac_f32_e32 v99, v89, v89
	v_fmac_f32_e32 v58, v55, v55
	v_fmac_f32_e32 v99, v88, v88
	v_fmac_f32_e32 v58, v53, v53
	v_fmac_f32_e32 v58, v42, v42
	ds_bpermute_b32 v16, v192, v99
	v_mul_f32_e32 v76, v48, v48
	s_waitcnt lgkmcnt(2)
	v_add_f32_e32 v30, v102, v30
	ds_bpermute_b32 v45, v192, v58
	v_fmac_f32_e32 v76, v49, v49
	s_waitcnt lgkmcnt(2)
	v_add_f32_e32 v15, v15, v47
	ds_bpermute_b32 v47, v193, v30
	v_fmac_f32_e32 v76, v37, v37
	v_fmac_f32_e32 v76, v33, v33
	s_waitcnt lgkmcnt(2)
	v_add_f32_e32 v16, v99, v16
	ds_bpermute_b32 v31, v192, v76
	s_waitcnt lgkmcnt(2)
	v_add_f32_e32 v45, v58, v45
	ds_bpermute_b32 v58, v193, v16
	s_waitcnt lgkmcnt(2)
	v_add_f32_e32 v30, v30, v47
	ds_bpermute_b32 v47, v193, v1
	s_waitcnt lgkmcnt(2)
	v_add_f32_e32 v31, v76, v31
	ds_bpermute_b32 v76, v195, v17
	s_waitcnt lgkmcnt(2)
	v_add_f32_e32 v16, v16, v58
	ds_bpermute_b32 v58, v193, v31
	s_waitcnt lgkmcnt(2)
; __device__ __forceinline__ void unit(LAS unsigned char* lds, const bf16* __restrict__ PROJ, bf16* __restrict__ MIXED, const float* __restrict__ subln_g, float lam, int R0, int seq, int h, int qb) {
;     ...
; #pragma unroll
;         for (int off = 1; off < 32; off <<= 1)
; #pragma unroll
;             for (int r = 0; r < 16; ++r) sq[r] += __shfl_xor(sq[r], off);
;         float gv[4];
; #pragma unroll
;         for (int d = 0; d < 4; ++d) gv[d] = subln_g[32 * d + r32] * 0.8f;
; #pragma unroll
;         for (int r = 0; r < 16; ++r) { const float rs = 1.f / sqrtf(sq[r] * (1.f / 128.f) + EPS);
	v_add_f32_e32 v1, v1, v47
	ds_bpermute_b32 v47, v193, v14
	ds_bpermute_b32 v59, v194, v16
	s_waitcnt lgkmcnt(3)
	v_add_f32_e32 v17, v17, v76
	s_waitcnt lgkmcnt(2)
	v_add_f32_e32 v31, v31, v58
	ds_bpermute_b32 v58, v193, v45
	s_waitcnt lgkmcnt(2)
	v_add_f32_e32 v14, v14, v47
	s_waitcnt lgkmcnt(1)
	v_add_f32_e32 v16, v16, v59
	ds_bpermute_b32 v47, v194, v29
	ds_bpermute_b32 v59, v194, v31
	s_waitcnt lgkmcnt(2)
	v_add_f32_e32 v45, v45, v58
	ds_bpermute_b32 v58, v193, v15
	ds_bpermute_b32 v75, v195, v16
	s_waitcnt lgkmcnt(3)
	v_add_f32_e32 v29, v29, v47
	s_waitcnt lgkmcnt(2)
	v_add_f32_e32 v31, v31, v59
	ds_bpermute_b32 v47, v194, v0
	ds_bpermute_b32 v59, v194, v45
	s_waitcnt lgkmcnt(3)
	v_add_f32_e32 v15, v15, v58
	ds_bpermute_b32 v58, v194, v30
	s_waitcnt lgkmcnt(3)
	v_add_f32_e32 v16, v16, v75
	s_waitcnt lgkmcnt(2)
	v_add_f32_e32 v0, v0, v47
	s_waitcnt lgkmcnt(1)
	v_add_f32_e32 v45, v45, v59
	ds_bpermute_b32 v47, v194, v27
	ds_bpermute_b32 v59, v194, v15
	s_waitcnt lgkmcnt(2)
	v_add_f32_e32 v30, v30, v58
	ds_bpermute_b32 v58, v194, v1
	ds_bpermute_b32 v75, v195, v31
	s_waitcnt lgkmcnt(3)
	v_add_f32_e32 v27, v27, v47
	ds_bpermute_b32 v47, v194, v19
	s_waitcnt lgkmcnt(3)
	v_add_f32_e32 v15, v15, v59
	ds_bpermute_b32 v59, v195, v30
	ds_bpermute_b32 v76, v195, v43
	s_waitcnt lgkmcnt(4)
	v_add_f32_e32 v1, v1, v58
	ds_bpermute_b32 v58, v194, v14
	s_waitcnt lgkmcnt(3)
	v_add_f32_e32 v19, v19, v47
	ds_bpermute_b32 v47, v195, v28
	s_waitcnt lgkmcnt(3)
	v_add_f32_e32 v30, v30, v59
	v_add_f32_e32 v31, v31, v75
	ds_bpermute_b32 v59, v195, v1
	ds_bpermute_b32 v75, v195, v45
	s_waitcnt lgkmcnt(4)
	v_add_f32_e32 v43, v43, v76
	ds_bpermute_b32 v76, v195, v46
	s_waitcnt lgkmcnt(4)
	v_add_f32_e32 v14, v14, v58
	ds_bpermute_b32 v58, v195, v29
	s_waitcnt lgkmcnt(4)
	v_add_f32_e32 v28, v28, v47
	ds_bpermute_b32 v47, v195, v44
	s_waitcnt lgkmcnt(4)
	v_add_f32_e32 v1, v1, v59
	s_waitcnt lgkmcnt(3)
	v_add_f32_e32 v75, v45, v75
	ds_bpermute_b32 v45, v195, v27
	ds_bpermute_b32 v59, v196, v16
	s_waitcnt lgkmcnt(4)
	v_add_f32_e32 v76, v46, v76
	ds_bpermute_b32 v46, v195, v19
	s_waitcnt lgkmcnt(4)
	v_add_f32_e32 v29, v29, v58
	ds_bpermute_b32 v58, v195, v0
	s_waitcnt lgkmcnt(4)
	v_add_f32_e32 v44, v44, v47
	ds_bpermute_b32 v47, v195, v14
	s_waitcnt lgkmcnt(4)
	v_add_f32_e32 v27, v27, v45
	s_waitcnt lgkmcnt(3)
	v_add_f32_e32 v77, v16, v59
	ds_bpermute_b32 v16, v196, v17
	ds_bpermute_b32 v45, v196, v28
	s_waitcnt lgkmcnt(4)
	v_add_f32_e32 v19, v19, v46
	ds_bpermute_b32 v46, v196, v29
	s_waitcnt lgkmcnt(4)
	v_add_f32_e32 v0, v0, v58
	ds_bpermute_b32 v58, v195, v15
	s_waitcnt lgkmcnt(4)
	v_add_f32_e32 v14, v14, v47
	ds_bpermute_b32 v47, v196, v30
	s_waitcnt lgkmcnt(4)
	v_add_f32_e32 v91, v17, v16
	s_waitcnt lgkmcnt(3)
	v_add_f32_e32 v92, v28, v45
	ds_bpermute_b32 v17, v196, v44
	ds_bpermute_b32 v28, v196, v0
	s_waitcnt lgkmcnt(4)
	v_add_f32_e32 v59, v29, v46
	ds_bpermute_b32 v16, v196, v43
	ds_bpermute_b32 v29, v196, v1
	s_waitcnt lgkmcnt(5)
	v_add_f32_e32 v15, v15, v58
	ds_bpermute_b32 v90, v196, v31
	s_waitcnt lgkmcnt(5)
	v_add_f32_e32 v58, v30, v47
	ds_bpermute_b32 v30, v196, v75
	s_waitcnt lgkmcnt(5)
	v_add_f32_e32 v45, v44, v17
	s_waitcnt lgkmcnt(4)
	v_add_f32_e32 v44, v0, v28
	ds_bpermute_b32 v0, v196, v76
	s_waitcnt lgkmcnt(4)
	v_add_f32_e32 v46, v43, v16
	s_waitcnt lgkmcnt(3)
	v_add_f32_e32 v43, v1, v29
	ds_bpermute_b32 v1, v196, v27
	s_waitcnt lgkmcnt(3)
	v_add_f32_e32 v47, v31, v90
	s_waitcnt lgkmcnt(2)
	v_add_f32_e32 v31, v75, v30
	s_waitcnt lgkmcnt(1)
	v_add_f32_e32 v30, v76, v0
	v_fmamk_f32 v0, v77, 0x3c000000, v189
	s_waitcnt lgkmcnt(0)
	v_add_f32_e32 v29, v27, v1
	v_mul_f32_e32 v1, 0x4f800000, v0
	v_cmp_gt_f32_e32 vcc, s58, v0
	ds_bpermute_b32 v16, v196, v19
	ds_bpermute_b32 v17, v196, v14
	v_cndmask_b32_e32 v0, v0, v1, vcc
	v_sqrt_f32_e32 v1, v0
	s_waitcnt vmcnt(2)
	v_mul_f32_e32 v27, 0x3f4ccccd, v60
	s_waitcnt lgkmcnt(1)
	v_add_f32_e32 v28, v19, v16
	s_waitcnt lgkmcnt(0)
	v_add_f32_e32 v16, v14, v17
	v_add_u32_e32 v60, -1, v1
	v_mul_f32_e32 v14, 0x3f4ccccd, v61
	v_fma_f32 v61, -v60, v1, v0
	v_cmp_ge_f32_e64 s[4:5], 0, v61
	v_add_u32_e32 v61, 1, v1
	ds_bpermute_b32 v75, v196, v15
	v_cndmask_b32_e64 v60, v1, v60, s[4:5]
	v_fma_f32 v1, -v61, v1, v0
	v_cmp_lt_f32_e64 s[4:5], 0, v1
	s_waitcnt vmcnt(1)
	v_mul_f32_e32 v19, 0x3f4ccccd, v62
	s_waitcnt vmcnt(0)
	v_mul_f32_e32 v17, 0x3f4ccccd, v63
	v_cndmask_b32_e64 v1, v60, v61, s[4:5]
	v_mul_f32_e32 v60, 0x37800000, v1
	v_cndmask_b32_e32 v1, v1, v60, vcc
	v_cmp_class_f32_e32 vcc, v0, v209
	s_waitcnt lgkmcnt(0)
; __device__ __forceinline__ unsigned f2bf(float f) { unsigned u = __builtin_bit_cast(unsigned, f); return (u + 0x7fffu + ((u >> 16) & 1u)) >> 16; }
; __device__ __forceinline__ int crow(int r, int hi) { return (r & 3) + 8 * (r >> 2) + 4 * hi; }
; __device__ __forceinline__ void unit(LAS unsigned char* lds, const bf16* __restrict__ PROJ, bf16* __restrict__ MIXED, const float* __restrict__ subln_g, float lam, int R0, int seq, int h, int qb) {
;     ...
;         for (int r = 0; r < 16; ++r) { const float rs = 1.f / sqrtf(sq[r] * (1.f / 128.f) + EPS);
;             bf16* op = MIXED + (size_t)(R0 + 128 * qb + 32 * g + crow(r, hi)) * DM + 1024 + h * 128 + r32;
; #pragma unroll
;             for (int d = 0; d < 4; ++d) op[32 * d] = (bf16)f2bf(o[d][r] * rs * gv[d]); }
	v_add_f32_e32 v15, v15, v75
	s_add_i32 s70, s70, s61
	v_cndmask_b32_e32 v1, v1, v0, vcc
	v_div_scale_f32 v60, s[4:5], v1, v1, 1.0
	v_rcp_f32_e32 v61, v60
	v_or_b32_e32 v0, s63, v171
	v_add_u32_e32 v0, s70, v0
	s_lshl_b32 s6, s62, 1
	v_fma_f32 v62, -v60, v61, 1.0
	v_fmac_f32_e32 v61, v62, v61
	v_div_scale_f32 v62, vcc, 1.0, v1, 1.0
	v_mul_f32_e32 v63, v62, v61
	v_fma_f32 v75, -v60, v63, v62
	v_fmac_f32_e32 v63, v75, v61
	v_fma_f32 v60, -v60, v63, v62
	v_div_fmas_f32 v60, v60, v61, v63
	v_div_fixup_f32 v62, v60, v1, 1.0
	v_ashrrev_i32_e32 v1, 31, v0
	v_lshlrev_b64 v[0:1], 12, v[0:1]
	v_lshl_add_u64 v[0:1], s[64:65], 0, v[0:1]
	v_lshl_add_u64 v[0:1], v[0:1], 0, s[6:7]
	v_lshlrev_b32_e32 v60, 1, v169
	v_mov_b32_e32 v61, v161
	v_lshl_add_u64 v[0:1], v[0:1], 0, v[60:61]
	v_mov_b32_e32 v250, v0
	v_mov_b32_e32 v251, v1
	v_lshrrev_b32_e32 v254, 7, v168
	v_lshlrev_b32_e32 v254, 13, v254
	v_add_u32_e32 v254, 0x19000, v254
	v_lshl_add_u32 v255, v190, 4, v254
	v_lshrrev_b32_e32 v252, 5, v190
	v_lshl_add_u32 v254, v252, 10, v254
	v_lshl_add_u32 v254, v169, 1, v254
	v_mul_f32_e32 v60, v85, v62
	v_mul_f32_e32 v60, v60, v14
	v_bfe_u32 v61, v60, 16, 1
	v_add3_u32 v60, v60, v61, s59
	ds_write_b16_d16_hi v254, v60 offset:0
	v_mul_f32_e32 v60, v87, v62
	v_mul_f32_e32 v60, v60, v27
	v_bfe_u32 v61, v60, 16, 1
	v_add3_u32 v60, v60, v61, s59
	ds_write_b16_d16_hi v254, v60 offset:64
	v_mul_f32_e32 v60, v89, v62
	v_mul_f32_e32 v60, v60, v19
	v_bfe_u32 v61, v60, 16, 1
	v_add3_u32 v60, v60, v61, s59
	v_fmamk_f32 v61, v91, 0x3c000000, v189
	v_mul_f32_e32 v63, 0x4f800000, v61
	v_cmp_gt_f32_e32 vcc, s58, v61
	ds_write_b16_d16_hi v254, v60 offset:128
	v_mul_f32_e32 v60, v88, v62
	v_cndmask_b32_e32 v61, v61, v63, vcc
	v_sqrt_f32_e32 v63, v61
	v_mul_f32_e32 v60, v60, v17
	v_fmamk_f32 v59, v59, 0x3c000000, v189
	v_fmamk_f32 v58, v58, 0x3c000000, v189
	v_add_u32_e32 v62, -1, v63
	v_fma_f32 v75, -v62, v63, v61
	v_cmp_ge_f32_e64 s[4:5], 0, v75
	v_add_u32_e32 v75, 1, v63
	v_fmamk_f32 v47, v47, 0x3c000000, v189
	v_cndmask_b32_e64 v62, v63, v62, s[4:5]
	v_fma_f32 v63, -v75, v63, v61
	v_cmp_lt_f32_e64 s[4:5], 0, v63
	v_fmamk_f32 v46, v46, 0x3c000000, v189
	v_fmamk_f32 v31, v31, 0x3c000000, v189
	v_cndmask_b32_e64 v62, v62, v75, s[4:5]
	v_mul_f32_e32 v63, 0x37800000, v62
	v_cndmask_b32_e32 v62, v62, v63, vcc
	v_cmp_class_f32_e32 vcc, v61, v209
	v_bfe_u32 v75, v60, 16, 1
	v_add3_u32 v60, v60, v75, s59
	v_cndmask_b32_e32 v61, v62, v61, vcc
	v_div_scale_f32 v62, s[4:5], v61, v61, 1.0
	v_rcp_f32_e32 v63, v62
	ds_write_b16_d16_hi v254, v60 offset:192
	s_mov_b64 s[4:5], 0x1000
	v_fmamk_f32 v30, v30, 0x3c000000, v189
	v_fma_f32 v60, -v62, v63, 1.0
	v_fmac_f32_e32 v63, v60, v63
	v_div_scale_f32 v60, vcc, 1.0, v61, 1.0
	v_mul_f32_e32 v75, v60, v63
	v_fma_f32 v76, -v62, v75, v60
	v_fmac_f32_e32 v75, v76, v63
	v_fma_f32 v60, -v62, v75, v60
	v_div_fmas_f32 v60, v60, v63, v75
	v_div_fixup_f32 v62, v60, v61, 1.0
	v_mul_f32_e32 v63, v86, v62
	v_mul_f32_e32 v63, v63, v14
	v_bfe_u32 v75, v63, 16, 1
	v_lshl_add_u64 v[60:61], v[0:1], 0, s[4:5]
	v_add3_u32 v63, v63, v75, s59
	ds_write_b16_d16_hi v254, v63 offset:256
	v_mul_f32_e32 v63, v84, v62
	v_mul_f32_e32 v63, v63, v27
	v_bfe_u32 v75, v63, 16, 1
	v_add3_u32 v63, v63, v75, s59
	ds_write_b16_d16_hi v254, v63 offset:320
	v_mul_f32_e32 v63, v83, v62
	v_mul_f32_e32 v63, v63, v19
	v_bfe_u32 v75, v63, 16, 1
	v_add3_u32 v63, v63, v75, s59
	v_fmamk_f32 v75, v92, 0x3c000000, v189
	v_mul_f32_e32 v76, 0x4f800000, v75
	v_cmp_gt_f32_e32 vcc, s58, v75
	ds_write_b16_d16_hi v254, v63 offset:384
	v_mul_f32_e32 v62, v82, v62
	v_cndmask_b32_e32 v75, v75, v76, vcc
	v_sqrt_f32_e32 v76, v75
	v_mul_f32_e32 v62, v62, v17
	v_fmamk_f32 v29, v29, 0x3c000000, v189
	v_add_u32_e32 v63, -1, v76
	v_fma_f32 v77, -v63, v76, v75
	v_cmp_ge_f32_e64 s[4:5], 0, v77
	v_add_u32_e32 v77, 1, v76
	s_nop 0
	v_cndmask_b32_e64 v63, v76, v63, s[4:5]
	v_fma_f32 v76, -v77, v76, v75
	v_cmp_lt_f32_e64 s[4:5], 0, v76
	s_nop 1
	v_cndmask_b32_e64 v63, v63, v77, s[4:5]
	v_mul_f32_e32 v76, 0x37800000, v63
	v_cndmask_b32_e32 v63, v63, v76, vcc
	v_cmp_class_f32_e32 vcc, v75, v209
	v_bfe_u32 v77, v62, 16, 1
	v_add3_u32 v62, v62, v77, s59
	v_cndmask_b32_e32 v63, v63, v75, vcc
	v_div_scale_f32 v75, s[4:5], v63, v63, 1.0
	v_rcp_f32_e32 v76, v75
	ds_write_b16_d16_hi v254, v62 offset:448
	v_fma_f32 v60, -v75, v76, 1.0
	v_fmac_f32_e32 v76, v60, v76
	v_div_scale_f32 v60, vcc, 1.0, v63, 1.0
	v_mul_f32_e32 v61, v60, v76
	v_fma_f32 v62, -v75, v61, v60
	v_fmac_f32_e32 v61, v62, v76
	v_fma_f32 v60, -v75, v61, v60
	v_div_fmas_f32 v60, v60, v76, v61
	v_div_fixup_f32 v62, v60, v63, 1.0
	v_mul_f32_e32 v63, v81, v62
	v_mul_f32_e32 v63, v63, v14
	v_bfe_u32 v75, v63, 16, 1
	v_lshl_add_u64 v[60:61], v[0:1], 0, s[8:9]
	v_add3_u32 v63, v63, v75, s59
	ds_write_b16_d16_hi v254, v63 offset:512
	v_mul_f32_e32 v63, v80, v62
	v_mul_f32_e32 v63, v63, v27
	v_bfe_u32 v75, v63, 16, 1
	v_add3_u32 v63, v63, v75, s59
	ds_write_b16_d16_hi v254, v63 offset:576
	v_mul_f32_e32 v63, v79, v62
	v_mul_f32_e32 v63, v63, v19
	v_bfe_u32 v75, v63, 16, 1
	v_add3_u32 v63, v63, v75, s59
	v_mul_f32_e32 v75, 0x4f800000, v59
	v_cmp_gt_f32_e32 vcc, s58, v59
	ds_write_b16_d16_hi v254, v63 offset:640
	v_mul_f32_e32 v62, v78, v62
	v_cndmask_b32_e32 v59, v59, v75, vcc
	v_sqrt_f32_e32 v75, v59
	v_mul_f32_e32 v62, v62, v17
	v_add_u32_e32 v63, -1, v75
	v_fma_f32 v76, -v63, v75, v59
	v_cmp_ge_f32_e64 s[4:5], 0, v76
	v_add_u32_e32 v76, 1, v75
	s_nop 0
	v_cndmask_b32_e64 v63, v75, v63, s[4:5]
	v_fma_f32 v75, -v76, v75, v59
	v_cmp_lt_f32_e64 s[4:5], 0, v75
	s_nop 1
	v_cndmask_b32_e64 v63, v63, v76, s[4:5]
	v_mul_f32_e32 v75, 0x37800000, v63
	v_cndmask_b32_e32 v63, v63, v75, vcc
; __device__ __forceinline__ unsigned f2bf(float f) { unsigned u = __builtin_bit_cast(unsigned, f); return (u + 0x7fffu + ((u >> 16) & 1u)) >> 16; }
; __device__ __forceinline__ int crow(int r, int hi) { return (r & 3) + 8 * (r >> 2) + 4 * hi; }
; __device__ __forceinline__ void unit(LAS unsigned char* lds, const bf16* __restrict__ PROJ, bf16* __restrict__ MIXED, const float* __restrict__ subln_g, float lam, int R0, int seq, int h, int qb) {
;     ...
;         for (int r = 0; r < 16; ++r) { const float rs = 1.f / sqrtf(sq[r] * (1.f / 128.f) + EPS);
;             bf16* op = MIXED + (size_t)(R0 + 128 * qb + 32 * g + crow(r, hi)) * DM + 1024 + h * 128 + r32;
; #pragma unroll
;             for (int d = 0; d < 4; ++d) op[32 * d] = (bf16)f2bf(o[d][r] * rs * gv[d]); }
	v_cmp_class_f32_e32 vcc, v59, v209
	v_bfe_u32 v76, v62, 16, 1
	v_add3_u32 v62, v62, v76, s59
	v_cndmask_b32_e32 v59, v63, v59, vcc
	v_div_scale_f32 v63, s[4:5], v59, v59, 1.0
	v_rcp_f32_e32 v75, v63
	ds_write_b16_d16_hi v254, v62 offset:704
	s_mov_b64 s[4:5], 0x3000
	v_fma_f32 v60, -v63, v75, 1.0
	v_fmac_f32_e32 v75, v60, v75
	v_div_scale_f32 v60, vcc, 1.0, v59, 1.0
	v_mul_f32_e32 v61, v60, v75
	v_fma_f32 v62, -v63, v61, v60
	v_fmac_f32_e32 v61, v62, v75
	v_fma_f32 v60, -v63, v61, v60
	v_div_fmas_f32 v60, v60, v75, v61
	v_div_fixup_f32 v59, v60, v59, 1.0
	v_mul_f32_e32 v62, v68, v59
	v_mul_f32_e32 v62, v62, v14
	v_bfe_u32 v63, v62, 16, 1
	v_lshl_add_u64 v[60:61], v[0:1], 0, s[4:5]
	v_add3_u32 v62, v62, v63, s59
	ds_write_b16_d16_hi v254, v62 offset:768
	v_mul_f32_e32 v62, v67, v59
	v_mul_f32_e32 v62, v62, v27
	v_bfe_u32 v63, v62, 16, 1
	v_add3_u32 v62, v62, v63, s59
	ds_write_b16_d16_hi v254, v62 offset:832
	v_mul_f32_e32 v62, v66, v59
	v_mul_f32_e32 v62, v62, v19
	v_bfe_u32 v63, v62, 16, 1
	v_add3_u32 v62, v62, v63, s59
	v_mul_f32_e32 v63, 0x4f800000, v58
	v_cmp_gt_f32_e32 vcc, s58, v58
	ds_write_b16_d16_hi v254, v62 offset:896
	v_mul_f32_e32 v59, v65, v59
	v_cndmask_b32_e32 v58, v58, v63, vcc
	v_sqrt_f32_e32 v63, v58
	v_mul_f32_e32 v59, v59, v17
	v_add_u32_e32 v62, -1, v63
	v_fma_f32 v65, -v62, v63, v58
	v_cmp_ge_f32_e64 s[4:5], 0, v65
	v_add_u32_e32 v65, 1, v63
	s_nop 0
	v_cndmask_b32_e64 v62, v63, v62, s[4:5]
	v_fma_f32 v63, -v65, v63, v58
	v_cmp_lt_f32_e64 s[4:5], 0, v63
	s_nop 1
	v_cndmask_b32_e64 v62, v62, v65, s[4:5]
	v_mul_f32_e32 v63, 0x37800000, v62
	v_cndmask_b32_e32 v62, v62, v63, vcc
	v_cmp_class_f32_e32 vcc, v58, v209
	v_bfe_u32 v65, v59, 16, 1
	v_add3_u32 v59, v59, v65, s59
	v_cndmask_b32_e32 v58, v62, v58, vcc
	v_div_scale_f32 v62, s[4:5], v58, v58, 1.0
	v_rcp_f32_e32 v63, v62
	ds_write_b16_d16_hi v254, v59 offset:960
	s_mov_b64 s[4:5], 0x8000
	v_fma_f32 v59, -v62, v63, 1.0
	v_fmac_f32_e32 v63, v59, v63
	v_div_scale_f32 v59, vcc, 1.0, v58, 1.0
	v_mul_f32_e32 v60, v59, v63
	v_fma_f32 v61, -v62, v60, v59
	v_fmac_f32_e32 v60, v61, v63
	v_fma_f32 v59, -v62, v60, v59
	v_div_fmas_f32 v59, v59, v63, v60
	v_div_fixup_f32 v60, v59, v58, 1.0
	v_mul_f32_e32 v61, v64, v60
	v_mul_f32_e32 v61, v61, v14
	v_bfe_u32 v62, v61, 16, 1
	v_mul_f32_e32 v52, v52, v60
	v_lshl_add_u64 v[58:59], v[0:1], 0, s[4:5]
	v_add3_u32 v61, v61, v62, s59
	v_mul_f32_e32 v52, v52, v27
	ds_write_b16_d16_hi v254, v61 offset:2048
	v_bfe_u32 v61, v52, 16, 1
	v_mul_f32_e32 v51, v51, v60
	v_add3_u32 v52, v52, v61, s59
	v_mul_f32_e32 v51, v51, v19
	ds_write_b16_d16_hi v254, v52 offset:2112
	v_bfe_u32 v52, v51, 16, 1
	v_add3_u32 v51, v51, v52, s59
	v_mul_f32_e32 v52, 0x4f800000, v47
	v_cmp_gt_f32_e32 vcc, s58, v47
	ds_write_b16_d16_hi v254, v51 offset:2176
	v_mul_f32_e32 v50, v50, v60
	v_cndmask_b32_e32 v47, v47, v52, vcc
	v_sqrt_f32_e32 v52, v47
	v_mul_f32_e32 v50, v50, v17
	v_add_u32_e32 v51, -1, v52
	v_fma_f32 v60, -v51, v52, v47
	v_cmp_ge_f32_e64 s[4:5], 0, v60
	v_add_u32_e32 v60, 1, v52
	s_nop 0
	v_cndmask_b32_e64 v51, v52, v51, s[4:5]
	v_fma_f32 v52, -v60, v52, v47
	v_cmp_lt_f32_e64 s[4:5], 0, v52
	s_nop 1
	v_cndmask_b32_e64 v51, v51, v60, s[4:5]
	v_mul_f32_e32 v52, 0x37800000, v51
	v_cndmask_b32_e32 v51, v51, v52, vcc
	v_cmp_class_f32_e32 vcc, v47, v209
	v_bfe_u32 v60, v50, 16, 1
	v_add3_u32 v50, v50, v60, s59
	v_cndmask_b32_e32 v47, v51, v47, vcc
	v_div_scale_f32 v51, s[4:5], v47, v47, 1.0
	v_rcp_f32_e32 v52, v51
	ds_write_b16_d16_hi v254, v50 offset:2240
	s_mov_b64 s[4:5], 0x9000
	v_fma_f32 v50, -v51, v52, 1.0
	v_fmac_f32_e32 v52, v50, v52
	v_div_scale_f32 v50, vcc, 1.0, v47, 1.0
	v_mul_f32_e32 v58, v50, v52
	v_fma_f32 v59, -v51, v58, v50
	v_fmac_f32_e32 v58, v59, v52
	v_fma_f32 v50, -v51, v58, v50
	v_div_fmas_f32 v50, v50, v52, v58
	v_div_fixup_f32 v47, v50, v47, 1.0
	v_mul_f32_e32 v49, v49, v47
	v_mul_f32_e32 v49, v49, v14
	v_bfe_u32 v52, v49, 16, 1
	v_mul_f32_e32 v48, v48, v47
	v_lshl_add_u64 v[50:51], v[0:1], 0, s[4:5]
	v_add3_u32 v49, v49, v52, s59
	v_mul_f32_e32 v48, v48, v27
	ds_write_b16_d16_hi v254, v49 offset:2304
	v_bfe_u32 v49, v48, 16, 1
	v_mul_f32_e32 v37, v37, v47
	v_add3_u32 v48, v48, v49, s59
	v_mul_f32_e32 v37, v37, v19
	ds_write_b16_d16_hi v254, v48 offset:2368
	v_bfe_u32 v48, v37, 16, 1
	v_add3_u32 v37, v37, v48, s59
	v_mul_f32_e32 v48, 0x4f800000, v46
	v_cmp_gt_f32_e32 vcc, s58, v46
	ds_write_b16_d16_hi v254, v37 offset:2432
	v_mul_f32_e32 v33, v33, v47
	v_cndmask_b32_e32 v46, v46, v48, vcc
	v_sqrt_f32_e32 v48, v46
	v_mul_f32_e32 v33, v33, v17
	v_add_u32_e32 v37, -1, v48
	v_fma_f32 v47, -v37, v48, v46
	v_cmp_ge_f32_e64 s[4:5], 0, v47
	v_add_u32_e32 v47, 1, v48
	s_nop 0
	v_cndmask_b32_e64 v37, v48, v37, s[4:5]
	v_fma_f32 v48, -v47, v48, v46
	v_cmp_lt_f32_e64 s[4:5], 0, v48
	v_bfe_u32 v48, v33, 16, 1
	v_add3_u32 v33, v33, v48, s59
	v_cndmask_b32_e64 v37, v37, v47, s[4:5]
	v_mul_f32_e32 v47, 0x37800000, v37
	v_cndmask_b32_e32 v37, v37, v47, vcc
	v_cmp_class_f32_e32 vcc, v46, v209
	ds_write_b16_d16_hi v254, v33 offset:2496
	s_nop 0
	v_cndmask_b32_e32 v37, v37, v46, vcc
	v_div_scale_f32 v46, s[4:5], v37, v37, 1.0
	v_rcp_f32_e32 v47, v46
	s_mov_b64 s[4:5], 0xa000
	v_fma_f32 v33, -v46, v47, 1.0
	v_fmac_f32_e32 v47, v33, v47
	v_div_scale_f32 v33, vcc, 1.0, v37, 1.0
	v_mul_f32_e32 v48, v33, v47
	v_fma_f32 v49, -v46, v48, v33
	v_fmac_f32_e32 v48, v49, v47
	v_fma_f32 v33, -v46, v48, v33
	v_div_fmas_f32 v33, v33, v47, v48
	v_div_fixup_f32 v33, v33, v37, 1.0
	v_mul_f32_e32 v32, v32, v33
	v_mul_f32_e32 v32, v32, v14
	v_bfe_u32 v37, v32, 16, 1
	v_mul_f32_e32 v21, v21, v33
	v_lshl_add_u64 v[46:47], v[0:1], 0, s[4:5]
	v_add3_u32 v32, v32, v37, s59
; __device__ __forceinline__ unsigned f2bf(float f) { unsigned u = __builtin_bit_cast(unsigned, f); return (u + 0x7fffu + ((u >> 16) & 1u)) >> 16; }
; __device__ __forceinline__ int crow(int r, int hi) { return (r & 3) + 8 * (r >> 2) + 4 * hi; }
; __device__ __forceinline__ void unit(LAS unsigned char* lds, const bf16* __restrict__ PROJ, bf16* __restrict__ MIXED, const float* __restrict__ subln_g, float lam, int R0, int seq, int h, int qb) {
;     ...
;         for (int r = 0; r < 16; ++r) { const float rs = 1.f / sqrtf(sq[r] * (1.f / 128.f) + EPS);
;             bf16* op = MIXED + (size_t)(R0 + 128 * qb + 32 * g + crow(r, hi)) * DM + 1024 + h * 128 + r32;
; #pragma unroll
;             for (int d = 0; d < 4; ++d) op[32 * d] = (bf16)f2bf(o[d][r] * rs * gv[d]); }
	v_mul_f32_e32 v21, v21, v27
	ds_write_b16_d16_hi v254, v32 offset:2560
	v_bfe_u32 v32, v21, 16, 1
	v_mul_f32_e32 v20, v20, v33
	v_add3_u32 v21, v21, v32, s59
	v_mul_f32_e32 v20, v20, v19
	ds_write_b16_d16_hi v254, v21 offset:2624
	v_bfe_u32 v21, v20, 16, 1
	v_add3_u32 v20, v20, v21, s59
	v_fmamk_f32 v21, v45, 0x3c000000, v189
	v_mul_f32_e32 v32, 0x4f800000, v21
	v_cmp_gt_f32_e32 vcc, s58, v21
	ds_write_b16_d16_hi v254, v20 offset:2688
	v_mul_f32_e32 v20, v38, v33
	v_cndmask_b32_e32 v21, v21, v32, vcc
	v_sqrt_f32_e32 v32, v21
	v_mul_f32_e32 v20, v20, v17
	v_add_u32_e32 v33, -1, v32
	v_fma_f32 v37, -v33, v32, v21
	v_cmp_ge_f32_e64 s[4:5], 0, v37
	v_add_u32_e32 v37, 1, v32
	s_nop 0
	v_cndmask_b32_e64 v33, v32, v33, s[4:5]
	v_fma_f32 v32, -v37, v32, v21
	v_cmp_lt_f32_e64 s[4:5], 0, v32
	s_nop 1
	v_cndmask_b32_e64 v32, v33, v37, s[4:5]
	v_mul_f32_e32 v33, 0x37800000, v32
	v_cndmask_b32_e32 v32, v32, v33, vcc
	v_cmp_class_f32_e32 vcc, v21, v209
	v_bfe_u32 v37, v20, 16, 1
	v_add3_u32 v20, v20, v37, s59
	v_cndmask_b32_e32 v21, v32, v21, vcc
	v_div_scale_f32 v32, s[4:5], v21, v21, 1.0
	v_rcp_f32_e32 v33, v32
	ds_write_b16_d16_hi v254, v20 offset:2752
	s_mov_b64 s[4:5], 0xb000
	v_fma_f32 v20, -v32, v33, 1.0
	v_fmac_f32_e32 v33, v20, v33
	v_div_scale_f32 v20, vcc, 1.0, v21, 1.0
	v_mul_f32_e32 v37, v20, v33
	v_fma_f32 v38, -v32, v37, v20
	v_fmac_f32_e32 v37, v38, v33
	v_fma_f32 v20, -v32, v37, v20
	v_div_fmas_f32 v20, v20, v33, v37
	v_div_fixup_f32 v32, v20, v21, 1.0
	v_mul_f32_e32 v33, v36, v32
	v_mul_f32_e32 v33, v33, v14
	v_bfe_u32 v36, v33, 16, 1
	v_lshl_add_u64 v[20:21], v[0:1], 0, s[4:5]
	v_add3_u32 v33, v33, v36, s59
	ds_write_b16_d16_hi v254, v33 offset:2816
	v_mul_f32_e32 v33, v34, v32
	v_mul_f32_e32 v33, v33, v27
	v_bfe_u32 v34, v33, 16, 1
	v_add3_u32 v33, v33, v34, s59
	ds_write_b16_d16_hi v254, v33 offset:2880
	v_mul_f32_e32 v33, v35, v32
	v_mul_f32_e32 v33, v33, v19
	v_bfe_u32 v34, v33, 16, 1
	v_add3_u32 v33, v33, v34, s59
	v_fmamk_f32 v34, v44, 0x3c000000, v189
	v_mul_f32_e32 v35, 0x4f800000, v34
	v_cmp_gt_f32_e32 vcc, s58, v34
	v_mul_f32_e32 v22, v22, v32
	ds_write_b16_d16_hi v254, v33 offset:2944
	v_cndmask_b32_e32 v34, v34, v35, vcc
	v_sqrt_f32_e32 v35, v34
	v_mul_f32_e32 v22, v22, v17
	v_add_u32_e32 v32, -1, v35
	v_fma_f32 v33, -v32, v35, v34
	v_cmp_ge_f32_e64 s[4:5], 0, v33
	v_add_u32_e32 v33, 1, v35
	s_nop 0
	v_cndmask_b32_e64 v32, v35, v32, s[4:5]
	v_fma_f32 v35, -v33, v35, v34
	v_cmp_lt_f32_e64 s[4:5], 0, v35
	v_bfe_u32 v35, v22, 16, 1
	v_add3_u32 v22, v22, v35, s59
	v_cndmask_b32_e64 v32, v32, v33, s[4:5]
	v_mul_f32_e32 v33, 0x37800000, v32
	v_cndmask_b32_e32 v32, v32, v33, vcc
	v_cmp_class_f32_e32 vcc, v34, v209
	ds_write_b16_d16_hi v254, v22 offset:3008
	s_nop 0
	v_cndmask_b32_e32 v32, v32, v34, vcc
	v_div_scale_f32 v33, s[4:5], v32, v32, 1.0
	v_rcp_f32_e32 v34, v33
	s_nop 0
	v_fma_f32 v20, -v33, v34, 1.0
	v_fmac_f32_e32 v34, v20, v34
	v_div_scale_f32 v20, vcc, 1.0, v32, 1.0
	v_mul_f32_e32 v21, v20, v34
	v_fma_f32 v22, -v33, v21, v20
	v_fmac_f32_e32 v21, v22, v34
	v_fma_f32 v20, -v33, v21, v20
	v_div_fmas_f32 v20, v20, v34, v21
	v_div_fixup_f32 v22, v20, v32, 1.0
	v_mul_f32_e32 v32, v69, v22
	v_mul_f32_e32 v32, v32, v14
	v_bfe_u32 v33, v32, 16, 1
	v_lshl_add_u64 v[20:21], v[0:1], 0, s[10:11]
	v_add3_u32 v32, v32, v33, s59
	ds_write_b16_d16_hi v254, v32 offset:4096
	v_mul_f32_e32 v32, v72, v22
	v_mul_f32_e32 v32, v32, v27
	v_bfe_u32 v33, v32, 16, 1
	v_add3_u32 v32, v32, v33, s59
	ds_write_b16_d16_hi v254, v32 offset:4160
	v_mul_f32_e32 v32, v74, v22
	v_mul_f32_e32 v32, v32, v19
	v_bfe_u32 v33, v32, 16, 1
	v_add3_u32 v32, v32, v33, s59
	v_fmamk_f32 v33, v43, 0x3c000000, v189
	v_mul_f32_e32 v34, 0x4f800000, v33
	v_cmp_gt_f32_e32 vcc, s58, v33
	ds_write_b16_d16_hi v254, v32 offset:4224
	v_mul_f32_e32 v22, v73, v22
	v_cndmask_b32_e32 v33, v33, v34, vcc
	v_sqrt_f32_e32 v34, v33
	v_mul_f32_e32 v22, v22, v17
	v_add_u32_e32 v32, -1, v34
	v_fma_f32 v35, -v32, v34, v33
	v_cmp_ge_f32_e64 s[4:5], 0, v35
	v_add_u32_e32 v35, 1, v34
	s_nop 0
	v_cndmask_b32_e64 v32, v34, v32, s[4:5]
	v_fma_f32 v34, -v35, v34, v33
	v_cmp_lt_f32_e64 s[4:5], 0, v34
	s_nop 1
	v_cndmask_b32_e64 v32, v32, v35, s[4:5]
	v_mul_f32_e32 v34, 0x37800000, v32
	v_cndmask_b32_e32 v32, v32, v34, vcc
	v_cmp_class_f32_e32 vcc, v33, v209
	v_bfe_u32 v35, v22, 16, 1
	v_add3_u32 v22, v22, v35, s59
	v_cndmask_b32_e32 v32, v32, v33, vcc
	v_div_scale_f32 v33, s[4:5], v32, v32, 1.0
	v_rcp_f32_e32 v34, v33
	ds_write_b16_d16_hi v254, v22 offset:4288
	v_fma_f32 v20, -v33, v34, 1.0
	v_fmac_f32_e32 v34, v20, v34
	v_div_scale_f32 v20, vcc, 1.0, v32, 1.0
	v_mul_f32_e32 v21, v20, v34
	v_fma_f32 v22, -v33, v21, v20
	v_fmac_f32_e32 v21, v22, v34
	v_fma_f32 v20, -v33, v21, v20
	v_div_fmas_f32 v20, v20, v34, v21
	v_div_fixup_f32 v22, v20, v32, 1.0
	v_mul_f32_e32 v32, v71, v22
	v_mul_f32_e32 v32, v32, v14
	v_bfe_u32 v33, v32, 16, 1
	v_lshl_add_u64 v[20:21], v[0:1], 0, s[12:13]
	v_add3_u32 v32, v32, v33, s59
	ds_write_b16_d16_hi v254, v32 offset:4352
	v_mul_f32_e32 v32, v70, v22
	v_mul_f32_e32 v32, v32, v27
	v_bfe_u32 v33, v32, 16, 1
	v_add3_u32 v32, v32, v33, s59
	ds_write_b16_d16_hi v254, v32 offset:4416
	v_mul_f32_e32 v32, v57, v22
	v_mul_f32_e32 v32, v32, v19
	v_bfe_u32 v33, v32, 16, 1
	v_add3_u32 v32, v32, v33, s59
	v_mul_f32_e32 v33, 0x4f800000, v31
	v_cmp_gt_f32_e32 vcc, s58, v31
	ds_write_b16_d16_hi v254, v32 offset:4480
	v_mul_f32_e32 v22, v56, v22
	v_cndmask_b32_e32 v31, v31, v33, vcc
	v_sqrt_f32_e32 v33, v31
	v_mul_f32_e32 v22, v22, v17
	v_add_u32_e32 v32, -1, v33
	v_fma_f32 v34, -v32, v33, v31
	v_cmp_ge_f32_e64 s[4:5], 0, v34
	v_add_u32_e32 v34, 1, v33
	s_nop 0
; __device__ __forceinline__ unsigned f2bf(float f) { unsigned u = __builtin_bit_cast(unsigned, f); return (u + 0x7fffu + ((u >> 16) & 1u)) >> 16; }
; __device__ __forceinline__ int crow(int r, int hi) { return (r & 3) + 8 * (r >> 2) + 4 * hi; }
; __device__ __forceinline__ void unit(LAS unsigned char* lds, const bf16* __restrict__ PROJ, bf16* __restrict__ MIXED, const float* __restrict__ subln_g, float lam, int R0, int seq, int h, int qb) {
;     ...
;         for (int r = 0; r < 16; ++r) { const float rs = 1.f / sqrtf(sq[r] * (1.f / 128.f) + EPS);
;             bf16* op = MIXED + (size_t)(R0 + 128 * qb + 32 * g + crow(r, hi)) * DM + 1024 + h * 128 + r32;
; #pragma unroll
;             for (int d = 0; d < 4; ++d) op[32 * d] = (bf16)f2bf(o[d][r] * rs * gv[d]); }
	v_cndmask_b32_e64 v32, v33, v32, s[4:5]
	v_fma_f32 v33, -v34, v33, v31
	v_cmp_lt_f32_e64 s[4:5], 0, v33
	s_nop 1
	v_cndmask_b32_e64 v32, v32, v34, s[4:5]
	v_mul_f32_e32 v33, 0x37800000, v32
	v_cndmask_b32_e32 v32, v32, v33, vcc
	v_cmp_class_f32_e32 vcc, v31, v209
	v_bfe_u32 v34, v22, 16, 1
	v_add3_u32 v22, v22, v34, s59
	v_cndmask_b32_e32 v31, v32, v31, vcc
	v_div_scale_f32 v32, s[4:5], v31, v31, 1.0
	v_rcp_f32_e32 v33, v32
	ds_write_b16_d16_hi v254, v22 offset:4544
	v_fma_f32 v20, -v32, v33, 1.0
	v_fmac_f32_e32 v33, v20, v33
	v_div_scale_f32 v20, vcc, 1.0, v31, 1.0
	v_mul_f32_e32 v21, v20, v33
	v_fma_f32 v22, -v32, v21, v20
	v_fmac_f32_e32 v21, v22, v33
	v_fma_f32 v20, -v32, v21, v20
	v_div_fmas_f32 v20, v20, v33, v21
	v_div_fixup_f32 v22, v20, v31, 1.0
	v_mul_f32_e32 v31, v55, v22
	v_mul_f32_e32 v31, v14, v31
	v_bfe_u32 v32, v31, 16, 1
	v_lshl_add_u64 v[20:21], v[0:1], 0, s[14:15]
	v_add3_u32 v31, v31, v32, s59
	ds_write_b16_d16_hi v254, v31 offset:4608
	v_mul_f32_e32 v31, v54, v22
	v_mul_f32_e32 v31, v31, v27
	v_bfe_u32 v32, v31, 16, 1
	v_add3_u32 v31, v31, v32, s59
	ds_write_b16_d16_hi v254, v31 offset:4672
	v_mul_f32_e32 v31, v53, v22
	v_mul_f32_e32 v31, v31, v19
	v_bfe_u32 v32, v31, 16, 1
	v_add3_u32 v31, v31, v32, s59
	v_mul_f32_e32 v32, 0x4f800000, v30
	v_cmp_gt_f32_e32 vcc, s58, v30
	ds_write_b16_d16_hi v254, v31 offset:4736
	v_mul_f32_e32 v22, v42, v22
	v_cndmask_b32_e32 v30, v30, v32, vcc
	v_sqrt_f32_e32 v32, v30
	v_mul_f32_e32 v22, v22, v17
	v_add_u32_e32 v31, -1, v32
	v_fma_f32 v33, -v31, v32, v30
	v_cmp_ge_f32_e64 s[4:5], 0, v33
	v_add_u32_e32 v33, 1, v32
	s_nop 0
	v_cndmask_b32_e64 v31, v32, v31, s[4:5]
	v_fma_f32 v32, -v33, v32, v30
	v_cmp_lt_f32_e64 s[4:5], 0, v32
	s_nop 1
	v_cndmask_b32_e64 v31, v31, v33, s[4:5]
	v_mul_f32_e32 v32, 0x37800000, v31
	v_cndmask_b32_e32 v31, v31, v32, vcc
	v_cmp_class_f32_e32 vcc, v30, v209
	v_bfe_u32 v33, v22, 16, 1
	v_add3_u32 v22, v22, v33, s59
	v_cndmask_b32_e32 v30, v31, v30, vcc
	v_div_scale_f32 v31, s[4:5], v30, v30, 1.0
	v_rcp_f32_e32 v32, v31
	ds_write_b16_d16_hi v254, v22 offset:4800
	v_fma_f32 v20, -v31, v32, 1.0
	v_fmac_f32_e32 v32, v20, v32
	v_div_scale_f32 v20, vcc, 1.0, v30, 1.0
	v_mul_f32_e32 v21, v20, v32
	v_fma_f32 v22, -v31, v21, v20
	v_fmac_f32_e32 v21, v22, v32
	v_fma_f32 v20, -v31, v21, v20
	v_div_fmas_f32 v20, v20, v32, v21
	v_div_fixup_f32 v22, v20, v30, 1.0
	v_mul_f32_e32 v30, v41, v22
	v_mul_f32_e32 v30, v14, v30
	v_bfe_u32 v31, v30, 16, 1
	v_lshl_add_u64 v[20:21], v[0:1], 0, s[16:17]
	v_add3_u32 v30, v30, v31, s59
	ds_write_b16_d16_hi v254, v30 offset:4864
	v_mul_f32_e32 v30, v40, v22
	v_mul_f32_e32 v30, v27, v30
	v_bfe_u32 v31, v30, 16, 1
	v_add3_u32 v30, v30, v31, s59
	ds_write_b16_d16_hi v254, v30 offset:4928
	v_mul_f32_e32 v30, v39, v22
	v_mul_f32_e32 v30, v30, v19
	v_bfe_u32 v31, v30, 16, 1
	v_add3_u32 v30, v30, v31, s59
	v_mul_f32_e32 v31, 0x4f800000, v29
	v_cmp_gt_f32_e32 vcc, s58, v29
	v_mul_f32_e32 v22, v26, v22
	ds_write_b16_d16_hi v254, v30 offset:4992
	v_cndmask_b32_e32 v29, v29, v31, vcc
	v_sqrt_f32_e32 v31, v29
	v_mul_f32_e32 v22, v22, v17
	v_add_u32_e32 v26, -1, v31
	v_fma_f32 v30, -v26, v31, v29
	v_cmp_ge_f32_e64 s[4:5], 0, v30
	v_add_u32_e32 v30, 1, v31
	s_nop 0
	v_cndmask_b32_e64 v26, v31, v26, s[4:5]
	v_fma_f32 v31, -v30, v31, v29
	v_cmp_lt_f32_e64 s[4:5], 0, v31
	v_bfe_u32 v31, v22, 16, 1
	v_add3_u32 v22, v22, v31, s59
	v_cndmask_b32_e64 v26, v26, v30, s[4:5]
	v_mul_f32_e32 v30, 0x37800000, v26
	v_cndmask_b32_e32 v26, v26, v30, vcc
	v_cmp_class_f32_e32 vcc, v29, v209
	ds_write_b16_d16_hi v254, v22 offset:5056
	s_nop 0
	v_cndmask_b32_e32 v26, v26, v29, vcc
	v_div_scale_f32 v29, s[4:5], v26, v26, 1.0
	v_rcp_f32_e32 v30, v29
	s_nop 0
	v_fma_f32 v20, -v29, v30, 1.0
	v_fmac_f32_e32 v30, v20, v30
	v_div_scale_f32 v20, vcc, 1.0, v26, 1.0
	v_mul_f32_e32 v21, v20, v30
	v_fma_f32 v22, -v29, v21, v20
	v_fmac_f32_e32 v21, v22, v30
	v_fma_f32 v20, -v29, v21, v20
	v_div_fmas_f32 v20, v20, v30, v21
	v_div_fixup_f32 v22, v20, v26, 1.0
	v_mul_f32_e32 v25, v25, v22
	v_mul_f32_e32 v25, v14, v25
	v_bfe_u32 v26, v25, 16, 1
	v_mul_f32_e32 v24, v24, v22
	v_lshl_add_u64 v[20:21], v[0:1], 0, s[18:19]
	v_add3_u32 v25, v25, v26, s59
	v_mul_f32_e32 v24, v27, v24
	ds_write_b16_d16_hi v254, v25 offset:6144
	v_bfe_u32 v25, v24, 16, 1
	v_mul_f32_e32 v23, v23, v22
	v_add3_u32 v24, v24, v25, s59
	v_mul_f32_e32 v23, v19, v23
	ds_write_b16_d16_hi v254, v24 offset:6208
	v_bfe_u32 v24, v23, 16, 1
	v_add3_u32 v23, v23, v24, s59
	v_fmamk_f32 v24, v28, 0x3c000000, v189
	v_mul_f32_e32 v25, 0x4f800000, v24
	v_cmp_gt_f32_e32 vcc, s58, v24
	v_mul_f32_e32 v18, v18, v22
	ds_write_b16_d16_hi v254, v23 offset:6272
	v_cndmask_b32_e32 v24, v24, v25, vcc
	v_sqrt_f32_e32 v25, v24
	v_mul_f32_e32 v18, v18, v17
	v_add_u32_e32 v22, -1, v25
	v_fma_f32 v23, -v22, v25, v24
	v_cmp_ge_f32_e64 s[4:5], 0, v23
	v_add_u32_e32 v23, 1, v25
	s_nop 0
	v_cndmask_b32_e64 v22, v25, v22, s[4:5]
	v_fma_f32 v25, -v23, v25, v24
	v_cmp_lt_f32_e64 s[4:5], 0, v25
	v_bfe_u32 v25, v18, 16, 1
	v_add3_u32 v18, v18, v25, s59
	v_cndmask_b32_e64 v22, v22, v23, s[4:5]
	v_mul_f32_e32 v23, 0x37800000, v22
	v_cndmask_b32_e32 v22, v22, v23, vcc
	v_cmp_class_f32_e32 vcc, v24, v209
	ds_write_b16_d16_hi v254, v18 offset:6336
	s_nop 0
	v_cndmask_b32_e32 v22, v22, v24, vcc
	v_div_scale_f32 v23, s[4:5], v22, v22, 1.0
	v_rcp_f32_e32 v24, v23
	s_nop 0
	v_fma_f32 v18, -v23, v24, 1.0
	v_fmac_f32_e32 v24, v18, v24
	v_div_scale_f32 v18, vcc, 1.0, v22, 1.0
	v_mul_f32_e32 v20, v18, v24
	v_fma_f32 v21, -v23, v20, v18
	v_fmac_f32_e32 v20, v21, v24
	v_fma_f32 v18, -v23, v20, v18
	v_div_fmas_f32 v18, v18, v24, v20
	v_div_fixup_f32 v18, v18, v22, 1.0
; __device__ __forceinline__ unsigned f2bf(float f) { unsigned u = __builtin_bit_cast(unsigned, f); return (u + 0x7fffu + ((u >> 16) & 1u)) >> 16; }
; __device__ __forceinline__ int crow(int r, int hi) { return (r & 3) + 8 * (r >> 2) + 4 * hi; }
; __device__ __forceinline__ void unit(LAS unsigned char* lds, const bf16* __restrict__ PROJ, bf16* __restrict__ MIXED, const float* __restrict__ subln_g, float lam, int R0, int seq, int h, int qb) {
;     ...
;         for (int r = 0; r < 16; ++r) { const float rs = 1.f / sqrtf(sq[r] * (1.f / 128.f) + EPS);
;             bf16* op = MIXED + (size_t)(R0 + 128 * qb + 32 * g + crow(r, hi)) * DM + 1024 + h * 128 + r32;
; #pragma unroll
;             for (int d = 0; d < 4; ++d) op[32 * d] = (bf16)f2bf(o[d][r] * rs * gv[d]); }
	v_mul_f32_e32 v12, v12, v18
	v_mul_f32_e32 v12, v14, v12
	v_bfe_u32 v22, v12, 16, 1
	v_mul_f32_e32 v11, v11, v18
	v_lshl_add_u64 v[20:21], v[0:1], 0, s[20:21]
	v_add3_u32 v12, v12, v22, s59
	v_mul_f32_e32 v11, v27, v11
	ds_write_b16_d16_hi v254, v12 offset:6400
	v_bfe_u32 v12, v11, 16, 1
	v_mul_f32_e32 v10, v10, v18
	v_add3_u32 v11, v11, v12, s59
	v_mul_f32_e32 v10, v19, v10
	ds_write_b16_d16_hi v254, v11 offset:6464
	v_bfe_u32 v11, v10, 16, 1
	v_add3_u32 v10, v10, v11, s59
	v_fmamk_f32 v11, v16, 0x3c000000, v189
	v_mul_f32_e32 v12, 0x4f800000, v11
	v_cmp_gt_f32_e32 vcc, s58, v11
	ds_write_b16_d16_hi v254, v10 offset:6528
	v_mul_f32_e32 v8, v8, v18
	v_cndmask_b32_e32 v11, v11, v12, vcc
	v_sqrt_f32_e32 v12, v11
	v_mul_f32_e32 v8, v17, v8
	v_add_u32_e32 v10, -1, v12
	v_fma_f32 v16, -v10, v12, v11
	v_cmp_ge_f32_e64 s[4:5], 0, v16
	v_add_u32_e32 v16, 1, v12
	s_nop 0
	v_cndmask_b32_e64 v10, v12, v10, s[4:5]
	v_fma_f32 v12, -v16, v12, v11
	v_cmp_lt_f32_e64 s[4:5], 0, v12
	s_nop 1
	v_cndmask_b32_e64 v10, v10, v16, s[4:5]
	v_mul_f32_e32 v12, 0x37800000, v10
	v_cndmask_b32_e32 v10, v10, v12, vcc
	v_cmp_class_f32_e32 vcc, v11, v209
	v_bfe_u32 v16, v8, 16, 1
	v_add3_u32 v8, v8, v16, s59
	v_cndmask_b32_e32 v10, v10, v11, vcc
	v_div_scale_f32 v11, s[4:5], v10, v10, 1.0
	v_rcp_f32_e32 v12, v11
	ds_write_b16_d16_hi v254, v8 offset:6592
	v_fma_f32 v8, -v11, v12, 1.0
	v_fmac_f32_e32 v12, v8, v12
	v_div_scale_f32 v8, vcc, 1.0, v10, 1.0
	v_mul_f32_e32 v16, v8, v12
	v_fma_f32 v18, -v11, v16, v8
	v_fmac_f32_e32 v16, v18, v12
	v_fma_f32 v8, -v11, v16, v8
	v_div_fmas_f32 v8, v8, v12, v16
	v_div_fixup_f32 v8, v8, v10, 1.0
	v_mul_f32_e32 v4, v4, v8
	v_mul_f32_e32 v4, v14, v4
	v_bfe_u32 v12, v4, 16, 1
	v_mul_f32_e32 v3, v3, v8
	v_lshl_add_u64 v[10:11], v[0:1], 0, s[22:23]
	v_add3_u32 v4, v4, v12, s59
	v_mul_f32_e32 v3, v27, v3
	ds_write_b16_d16_hi v254, v4 offset:6656
	v_bfe_u32 v4, v3, 16, 1
	v_mul_f32_e32 v2, v2, v8
	v_add3_u32 v3, v3, v4, s59
	v_mul_f32_e32 v2, v19, v2
	ds_write_b16_d16_hi v254, v3 offset:6720
	v_bfe_u32 v3, v2, 16, 1
	v_add3_u32 v2, v2, v3, s59
	v_fmamk_f32 v3, v15, 0x3c000000, v189
	v_mul_f32_e32 v4, 0x4f800000, v3
	v_cmp_gt_f32_e32 vcc, s58, v3
	ds_write_b16_d16_hi v254, v2 offset:6784
	v_mul_f32_e32 v2, v13, v8
	v_cndmask_b32_e32 v3, v3, v4, vcc
	v_sqrt_f32_e32 v4, v3
	v_mul_f32_e32 v2, v17, v2
	v_lshl_add_u64 v[0:1], v[0:1], 0, s[24:25]
	v_add_u32_e32 v8, -1, v4
	v_fma_f32 v12, -v8, v4, v3
	v_cmp_ge_f32_e64 s[4:5], 0, v12
	v_add_u32_e32 v12, 1, v4
	s_nop 0
	v_cndmask_b32_e64 v8, v4, v8, s[4:5]
	v_fma_f32 v4, -v12, v4, v3
	v_cmp_lt_f32_e64 s[4:5], 0, v4
	s_nop 1
	v_cndmask_b32_e64 v4, v8, v12, s[4:5]
	v_mul_f32_e32 v8, 0x37800000, v4
	v_cndmask_b32_e32 v4, v4, v8, vcc
	v_cmp_class_f32_e32 vcc, v3, v209
	v_bfe_u32 v12, v2, 16, 1
	v_add3_u32 v2, v2, v12, s59
	v_cndmask_b32_e32 v3, v4, v3, vcc
	v_div_scale_f32 v4, s[4:5], v3, v3, 1.0
	v_rcp_f32_e32 v8, v4
	ds_write_b16_d16_hi v254, v2 offset:6848
	v_fma_f32 v2, -v4, v8, 1.0
	v_fmac_f32_e32 v8, v2, v8
	v_div_scale_f32 v2, vcc, 1.0, v3, 1.0
	v_mul_f32_e32 v10, v2, v8
	v_fma_f32 v11, -v4, v10, v2
	v_fmac_f32_e32 v10, v11, v8
	v_fma_f32 v2, -v4, v10, v2
	v_div_fmas_f32 v2, v2, v8, v10
	v_div_fixup_f32 v2, v2, v3, 1.0
	v_mul_f32_e32 v3, v9, v2
	v_mul_f32_e32 v3, v14, v3
	v_bfe_u32 v4, v3, 16, 1
	v_add3_u32 v3, v3, v4, s59
	ds_write_b16_d16_hi v254, v3 offset:6912
	v_mul_f32_e32 v3, v6, v2
	v_mul_f32_e32 v3, v27, v3
	v_bfe_u32 v4, v3, 16, 1
	v_add3_u32 v3, v3, v4, s59
	ds_write_b16_d16_hi v254, v3 offset:6976
	v_mul_f32_e32 v3, v7, v2
	v_mul_f32_e32 v3, v19, v3
	v_bfe_u32 v4, v3, 16, 1
	v_mul_f32_e32 v2, v5, v2
	v_add3_u32 v3, v3, v4, s59
	v_mul_f32_e32 v2, v17, v2
	ds_write_b16_d16_hi v254, v3 offset:7040
	v_bfe_u32 v3, v2, 16, 1
	v_add3_u32 v2, v2, v3, s59
	ds_write_b16_d16_hi v254, v2 offset:7104
	v_lshrrev_b32_e32 v224, 4, v190
	v_and_b32_e32 v225, 15, v190
	v_lshlrev_b32_e32 v224, 12, v224
	v_lshl_add_u32 v224, v225, 4, v224
	v_mov_b32_e32 v225, 0
	v_lshl_add_u64 v[250:251], v[250:251], 0, v[224:225]
	v_lshlrev_b32_e32 v224, 14, v252
	v_lshl_add_u32 v224, v169, 1, v224
	v_sub_co_u32_e32 v250, vcc, v250, v224
	s_nop 1
	v_subbrev_co_u32_e32 v251, vcc, 0, v251, vcc
	s_mov_b64 s[4:5], 0x4000
	s_waitcnt lgkmcnt(0)
	ds_read_b128 v[224:227], v255
	ds_read_b128 v[228:231], v255 offset:1024
	ds_read_b128 v[232:235], v255 offset:2048
	ds_read_b128 v[236:239], v255 offset:3072
	s_waitcnt lgkmcnt(3)
	global_store_dwordx4 v[250:251], v[224:227], off offset:2048
	v_lshl_add_u64 v[250:251], v[250:251], 0, s[4:5]
	s_waitcnt lgkmcnt(2)
	global_store_dwordx4 v[250:251], v[228:231], off offset:2048
	v_lshl_add_u64 v[250:251], v[250:251], 0, s[4:5]
	s_waitcnt lgkmcnt(1)
	global_store_dwordx4 v[250:251], v[232:235], off offset:2048
	v_lshl_add_u64 v[250:251], v[250:251], 0, s[4:5]
	s_waitcnt lgkmcnt(0)
	global_store_dwordx4 v[250:251], v[236:239], off offset:2048
	v_lshl_add_u64 v[250:251], v[250:251], 0, s[4:5]
	ds_read_b128 v[224:227], v255 offset:4096
	ds_read_b128 v[228:231], v255 offset:5120
	ds_read_b128 v[232:235], v255 offset:6144
	ds_read_b128 v[236:239], v255 offset:7168
	s_waitcnt lgkmcnt(3)
	global_store_dwordx4 v[250:251], v[224:227], off offset:2048
	v_lshl_add_u64 v[250:251], v[250:251], 0, s[4:5]
	s_waitcnt lgkmcnt(2)
	global_store_dwordx4 v[250:251], v[228:231], off offset:2048
	v_lshl_add_u64 v[250:251], v[250:251], 0, s[4:5]
	s_waitcnt lgkmcnt(1)
	global_store_dwordx4 v[250:251], v[232:235], off offset:2048
	v_lshl_add_u64 v[250:251], v[250:251], 0, s[4:5]
	s_waitcnt lgkmcnt(0)
	global_store_dwordx4 v[250:251], v[236:239], off offset:2048
	v_lshl_add_u64 v[250:251], v[250:251], 0, s[4:5]
	s_branch .LBB0_249
